# K-loop head segment: ds_read burst issued before the 11 scalar pointer-select instructions (they only feed later stage DMAs), 4 GEMM loops
# baseline (speedup 1.0000x reference)
.LBB0_290:
	s_add_i32 vcc_hi, 0, 0x10000
	s_add_i32 s97, 0, 0x14000
	v_add_u32_e32 v154, vcc_hi, v169
	ds_read_b128 v[146:149], v154
	ds_read_b128 v[150:153], v154 offset:1024
	ds_read_b128 v[164:167], v154 offset:2048
	ds_read_b128 v[172:175], v154 offset:3072
	v_add_u32_e32 v154, s97, v169
	ds_read_b128 v[176:179], v154
	ds_read_b128 v[180:183], v154 offset:1024
	ds_read_b128 v[184:187], v154 offset:2048
	ds_read_b128 v[188:191], v154 offset:3072
	ds_read_b128 v[200:203], v171
	ds_read_b128 v[204:207], v171 offset:1024
	ds_read_b128 v[208:211], v171 offset:2048
	ds_read_b128 v[212:215], v171 offset:3072
	ds_read_b128 v[216:219], v171 offset:4096
	ds_read_b128 v[220:223], v171 offset:5120
	ds_read_b128 v[224:227], v171 offset:6144
	ds_read_b128 v[228:231], v171 offset:7168
	s_add_u32 s12, s60, s10
	s_addc_u32 s13, s61, s11
	s_add_u32 s12, s12, 0x100
	s_addc_u32 s13, s13, 0
	s_add_u32 s101, s28, s10
	s_addc_u32 vcc_lo, s29, s11
	s_cmpk_eq_i32 s10, 0xf00
	s_cselect_b32 s41, s63, s13
	s_cselect_b32 s40, s94, s12
	s_cselect_b32 s13, s67, vcc_lo
	s_cselect_b32 s12, s95, s101
	v_lshl_add_u64 v[196:197], v[142:143], 0, s[10:11]
	s_add_i32 m0, s81, 0xc000
	s_nop 0
	global_load_lds_dwordx4 v[196:197], off
	v_lshl_add_u64 v[196:197], v[144:145], 0, s[10:11]
	s_add_i32 m0, s81, 0xe000
	s_nop 0
	global_load_lds_dwordx4 v[196:197], off
	s_waitcnt vmcnt(8)
	s_waitcnt lgkmcnt(0)
	s_barrier
	s_setprio 1
	s_waitcnt lgkmcnt(0)
	v_mfma_f32_16x16x32_bf16 v[126:129], v[146:149], v[200:203], v[126:129]
	v_mfma_f32_16x16x32_bf16 v[122:125], v[164:167], v[200:203], v[122:125]
	v_mfma_f32_16x16x32_bf16 v[118:121], v[146:149], v[208:211], v[118:121]
	v_mfma_f32_16x16x32_bf16 v[114:117], v[164:167], v[208:211], v[114:117]
	v_mfma_f32_16x16x32_bf16 v[110:113], v[146:149], v[216:219], v[110:113]
	v_mfma_f32_16x16x32_bf16 v[106:109], v[164:167], v[216:219], v[106:109]
	v_mfma_f32_16x16x32_bf16 v[102:105], v[146:149], v[224:227], v[102:105]
	v_mfma_f32_16x16x32_bf16 v[98:101], v[164:167], v[224:227], v[98:101]
	v_mfma_f32_16x16x32_bf16 v[126:129], v[150:153], v[204:207], v[126:129]
	v_mfma_f32_16x16x32_bf16 v[122:125], v[172:175], v[204:207], v[122:125]
	v_mfma_f32_16x16x32_bf16 v[118:121], v[150:153], v[212:215], v[118:121]
	v_mfma_f32_16x16x32_bf16 v[114:117], v[172:175], v[212:215], v[114:117]
	v_mfma_f32_16x16x32_bf16 v[110:113], v[150:153], v[220:223], v[110:113]
	v_mfma_f32_16x16x32_bf16 v[106:109], v[172:175], v[220:223], v[106:109]
	v_mfma_f32_16x16x32_bf16 v[102:105], v[150:153], v[228:231], v[102:105]
	v_mfma_f32_16x16x32_bf16 v[98:101], v[172:175], v[228:231], v[98:101]
	s_setprio 0
	s_setprio 1
	v_mfma_f32_16x16x32_bf16 v[94:97], v[176:179], v[200:203], v[94:97]
	v_mfma_f32_16x16x32_bf16 v[90:93], v[184:187], v[200:203], v[90:93]
	v_mfma_f32_16x16x32_bf16 v[86:89], v[176:179], v[208:211], v[86:89]
	v_mfma_f32_16x16x32_bf16 v[82:85], v[184:187], v[208:211], v[82:85]
	v_mfma_f32_16x16x32_bf16 v[78:81], v[176:179], v[216:219], v[78:81]
	v_mfma_f32_16x16x32_bf16 v[74:77], v[184:187], v[216:219], v[74:77]
	v_mfma_f32_16x16x32_bf16 v[70:73], v[176:179], v[224:227], v[70:73]
	v_mfma_f32_16x16x32_bf16 v[66:69], v[184:187], v[224:227], v[66:69]
	v_mfma_f32_16x16x32_bf16 v[94:97], v[180:183], v[204:207], v[94:97]
	v_mfma_f32_16x16x32_bf16 v[90:93], v[188:191], v[204:207], v[90:93]
	v_mfma_f32_16x16x32_bf16 v[86:89], v[180:183], v[212:215], v[86:89]
	v_mfma_f32_16x16x32_bf16 v[82:85], v[188:191], v[212:215], v[82:85]
	v_mfma_f32_16x16x32_bf16 v[78:81], v[180:183], v[220:223], v[78:81]
	v_mfma_f32_16x16x32_bf16 v[74:77], v[188:191], v[220:223], v[74:77]
	v_mfma_f32_16x16x32_bf16 v[70:73], v[180:183], v[228:231], v[70:73]
	v_mfma_f32_16x16x32_bf16 v[66:69], v[188:191], v[228:231], v[66:69]
	s_setprio 0
	s_barrier
	s_add_i32 vcc_lo, vcc_hi, s80
	v_lshl_add_u64 v[196:197], s[12:13], 0, v[132:133]
	s_mov_b32 m0, vcc_lo
	ds_read_b128 v[200:203], v171 offset:16384
	ds_read_b128 v[204:207], v171 offset:17408
	ds_read_b128 v[208:211], v171 offset:18432
	ds_read_b128 v[212:215], v171 offset:19456
	ds_read_b128 v[216:219], v171 offset:20480
	ds_read_b128 v[220:223], v171 offset:21504
	ds_read_b128 v[224:227], v171 offset:22528
	ds_read_b128 v[228:231], v171 offset:23552
	global_load_lds_dwordx4 v[196:197], off
	s_add_i32 m0, vcc_lo, 0x2000
	s_add_u32 vcc_lo, s12, 0x80000
	v_lshl_add_u64 v[232:233], s[12:13], 0, v[136:137]
	s_addc_u32 vcc_hi, s13, 0
	s_add_i32 s97, s97, s80
	global_load_lds_dwordx4 v[232:233], off
	v_lshl_add_u64 v[234:235], vcc, 0, v[132:133]
	s_mov_b32 m0, s97
	v_lshl_add_u64 v[236:237], s[40:41], 0, v[134:135]
	global_load_lds_dwordx4 v[234:235], off
	v_lshl_add_u64 v[234:235], vcc, 0, v[136:137]
	s_add_i32 m0, s97, 0x2000
	s_nop 0
	global_load_lds_dwordx4 v[234:235], off
	v_lshl_add_u64 v[234:235], s[40:41], 0, v[130:131]
	s_mov_b32 m0, s81
	s_nop 0
	global_load_lds_dwordx4 v[234:235], off
	s_mov_b32 m0, s82
	s_nop 0
	global_load_lds_dwordx4 v[236:237], off
	s_waitcnt vmcnt(8)
	s_waitcnt lgkmcnt(0)
	s_barrier
	s_setprio 1
	s_waitcnt lgkmcnt(0)
	v_mfma_f32_16x16x32_bf16 v[62:65], v[146:149], v[200:203], v[62:65]
	v_mfma_f32_16x16x32_bf16 v[58:61], v[164:167], v[200:203], v[58:61]
	v_mfma_f32_16x16x32_bf16 v[54:57], v[146:149], v[208:211], v[54:57]
	v_mfma_f32_16x16x32_bf16 v[50:53], v[164:167], v[208:211], v[50:53]
	v_mfma_f32_16x16x32_bf16 v[46:49], v[146:149], v[216:219], v[46:49]
	v_mfma_f32_16x16x32_bf16 v[42:45], v[164:167], v[216:219], v[42:45]
	v_mfma_f32_16x16x32_bf16 v[38:41], v[146:149], v[224:227], v[38:41]
	v_mfma_f32_16x16x32_bf16 v[34:37], v[164:167], v[224:227], v[34:37]
	v_mfma_f32_16x16x32_bf16 v[62:65], v[150:153], v[204:207], v[62:65]
	v_mfma_f32_16x16x32_bf16 v[58:61], v[172:175], v[204:207], v[58:61]
	v_mfma_f32_16x16x32_bf16 v[54:57], v[150:153], v[212:215], v[54:57]
	v_mfma_f32_16x16x32_bf16 v[50:53], v[172:175], v[212:215], v[50:53]
	v_mfma_f32_16x16x32_bf16 v[46:49], v[150:153], v[220:223], v[46:49]
	v_mfma_f32_16x16x32_bf16 v[42:45], v[172:175], v[220:223], v[42:45]
	v_mfma_f32_16x16x32_bf16 v[38:41], v[150:153], v[228:231], v[38:41]
	v_mfma_f32_16x16x32_bf16 v[34:37], v[172:175], v[228:231], v[34:37]
	s_setprio 0
	s_setprio 1
	v_mfma_f32_16x16x32_bf16 v[30:33], v[176:179], v[200:203], v[30:33]
	v_mfma_f32_16x16x32_bf16 v[26:29], v[184:187], v[200:203], v[26:29]
	v_mfma_f32_16x16x32_bf16 v[22:25], v[176:179], v[208:211], v[22:25]
	v_mfma_f32_16x16x32_bf16 v[18:21], v[184:187], v[208:211], v[18:21]
	v_mfma_f32_16x16x32_bf16 v[14:17], v[176:179], v[216:219], v[14:17]
	v_mfma_f32_16x16x32_bf16 v[10:13], v[184:187], v[216:219], v[10:13]
	v_mfma_f32_16x16x32_bf16 v[6:9], v[176:179], v[224:227], v[6:9]
	v_mfma_f32_16x16x32_bf16 v[2:5], v[184:187], v[224:227], v[2:5]
	v_mfma_f32_16x16x32_bf16 v[30:33], v[180:183], v[204:207], v[30:33]
	v_mfma_f32_16x16x32_bf16 v[26:29], v[188:191], v[204:207], v[26:29]
	v_mfma_f32_16x16x32_bf16 v[22:25], v[180:183], v[212:215], v[22:25]
	v_mfma_f32_16x16x32_bf16 v[18:21], v[188:191], v[212:215], v[18:21]
	v_mfma_f32_16x16x32_bf16 v[14:17], v[180:183], v[220:223], v[14:17]
	v_mfma_f32_16x16x32_bf16 v[10:13], v[188:191], v[220:223], v[10:13]
	v_mfma_f32_16x16x32_bf16 v[6:9], v[180:183], v[228:231], v[6:9]
	v_mfma_f32_16x16x32_bf16 v[2:5], v[188:191], v[228:231], v[2:5]
	s_setprio 0
	s_barrier
	s_add_i32 s97, 0, 0x18000
	v_add_u32_e32 v154, s97, v169
	s_add_i32 vcc_lo, 0, 0x1c000
	ds_read_b128 v[146:149], v154
	ds_read_b128 v[150:153], v154 offset:1024
	ds_read_b128 v[164:167], v154 offset:2048
	ds_read_b128 v[172:175], v154 offset:3072
	v_add_u32_e32 v154, vcc_lo, v169
	ds_read_b128 v[176:179], v154
	ds_read_b128 v[180:183], v154 offset:1024
	ds_read_b128 v[184:187], v154 offset:2048
	ds_read_b128 v[188:191], v154 offset:3072
	s_add_u32 s40, s40, 0x80000
	s_addc_u32 s41, s41, 0
	s_mov_b32 m0, s83
	v_lshl_add_u64 v[238:239], s[40:41], 0, v[130:131]
	ds_read_b128 v[200:203], v171 offset:32768
	ds_read_b128 v[204:207], v171 offset:33792
	ds_read_b128 v[208:211], v171 offset:34816
	ds_read_b128 v[212:215], v171 offset:35840
	ds_read_b128 v[216:219], v171 offset:36864
	ds_read_b128 v[220:223], v171 offset:37888
	ds_read_b128 v[224:227], v171 offset:38912
	ds_read_b128 v[228:231], v171 offset:39936
	global_load_lds_dwordx4 v[238:239], off
	v_lshl_add_u64 v[238:239], s[40:41], 0, v[134:135]
	s_mov_b32 m0, s84
	s_nop 0
	global_load_lds_dwordx4 v[238:239], off
	s_waitcnt vmcnt(8)
	s_waitcnt lgkmcnt(0)
	s_barrier
	s_setprio 1
	s_waitcnt lgkmcnt(0)
	v_mfma_f32_16x16x32_bf16 v[126:129], v[146:149], v[200:203], v[126:129]
	v_mfma_f32_16x16x32_bf16 v[122:125], v[164:167], v[200:203], v[122:125]
	v_mfma_f32_16x16x32_bf16 v[118:121], v[146:149], v[208:211], v[118:121]
	v_mfma_f32_16x16x32_bf16 v[114:117], v[164:167], v[208:211], v[114:117]
	v_mfma_f32_16x16x32_bf16 v[110:113], v[146:149], v[216:219], v[110:113]
	v_mfma_f32_16x16x32_bf16 v[106:109], v[164:167], v[216:219], v[106:109]
	v_mfma_f32_16x16x32_bf16 v[102:105], v[146:149], v[224:227], v[102:105]
	v_mfma_f32_16x16x32_bf16 v[98:101], v[164:167], v[224:227], v[98:101]
	v_mfma_f32_16x16x32_bf16 v[126:129], v[150:153], v[204:207], v[126:129]
	v_mfma_f32_16x16x32_bf16 v[122:125], v[172:175], v[204:207], v[122:125]
	v_mfma_f32_16x16x32_bf16 v[118:121], v[150:153], v[212:215], v[118:121]
	v_mfma_f32_16x16x32_bf16 v[114:117], v[172:175], v[212:215], v[114:117]
	v_mfma_f32_16x16x32_bf16 v[110:113], v[150:153], v[220:223], v[110:113]
	v_mfma_f32_16x16x32_bf16 v[106:109], v[172:175], v[220:223], v[106:109]
	v_mfma_f32_16x16x32_bf16 v[102:105], v[150:153], v[228:231], v[102:105]
	v_mfma_f32_16x16x32_bf16 v[98:101], v[172:175], v[228:231], v[98:101]
	s_setprio 0
	s_setprio 1
	v_mfma_f32_16x16x32_bf16 v[94:97], v[176:179], v[200:203], v[94:97]
	v_mfma_f32_16x16x32_bf16 v[90:93], v[184:187], v[200:203], v[90:93]
	v_mfma_f32_16x16x32_bf16 v[86:89], v[176:179], v[208:211], v[86:89]
	v_mfma_f32_16x16x32_bf16 v[82:85], v[184:187], v[208:211], v[82:85]
	v_mfma_f32_16x16x32_bf16 v[78:81], v[176:179], v[216:219], v[78:81]
	v_mfma_f32_16x16x32_bf16 v[74:77], v[184:187], v[216:219], v[74:77]
	v_mfma_f32_16x16x32_bf16 v[70:73], v[176:179], v[224:227], v[70:73]
	v_mfma_f32_16x16x32_bf16 v[66:69], v[184:187], v[224:227], v[66:69]
	v_mfma_f32_16x16x32_bf16 v[94:97], v[180:183], v[204:207], v[94:97]
	v_mfma_f32_16x16x32_bf16 v[90:93], v[188:191], v[204:207], v[90:93]
	v_mfma_f32_16x16x32_bf16 v[86:89], v[180:183], v[212:215], v[86:89]
	v_mfma_f32_16x16x32_bf16 v[82:85], v[188:191], v[212:215], v[82:85]
	v_mfma_f32_16x16x32_bf16 v[78:81], v[180:183], v[220:223], v[78:81]
	v_mfma_f32_16x16x32_bf16 v[74:77], v[188:191], v[220:223], v[74:77]
	v_mfma_f32_16x16x32_bf16 v[70:73], v[180:183], v[228:231], v[70:73]
	v_mfma_f32_16x16x32_bf16 v[66:69], v[188:191], v[228:231], v[66:69]
	s_setprio 0
	s_barrier
	s_add_i32 s40, s97, s80
	v_lshl_add_u64 v[196:197], v[196:197], 0, s[34:35]
	s_mov_b32 m0, s40
	ds_read_b128 v[200:203], v171 offset:49152
	ds_read_b128 v[204:207], v171 offset:50176
	ds_read_b128 v[208:211], v171 offset:51200
	ds_read_b128 v[212:215], v171 offset:52224
	ds_read_b128 v[216:219], v171 offset:53248
	ds_read_b128 v[220:223], v171 offset:54272
	ds_read_b128 v[224:227], v171 offset:55296
	ds_read_b128 v[228:231], v171 offset:56320
	global_load_lds_dwordx4 v[196:197], off
	s_add_i32 m0, s40, 0x2000
	s_add_u32 s12, s12, 0x80080
	v_lshl_add_u64 v[196:197], v[232:233], 0, s[34:35]
	s_addc_u32 s13, s13, 0
	s_add_i32 s40, vcc_lo, s80
	global_load_lds_dwordx4 v[196:197], off
	v_lshl_add_u64 v[196:197], s[12:13], 0, v[132:133]
	s_mov_b32 m0, s40
	s_nop 0
	global_load_lds_dwordx4 v[196:197], off
	v_lshl_add_u64 v[196:197], s[12:13], 0, v[136:137]
	s_add_i32 m0, s40, 0x2000
	s_nop 0
	global_load_lds_dwordx4 v[196:197], off
	v_lshl_add_u64 v[196:197], v[234:235], 0, s[34:35]
	s_mov_b32 m0, s85
	s_nop 0
	global_load_lds_dwordx4 v[196:197], off
	v_lshl_add_u64 v[196:197], v[236:237], 0, s[34:35]
	s_mov_b32 m0, s86
	s_nop 0
	global_load_lds_dwordx4 v[196:197], off
	s_waitcnt vmcnt(8)
	s_waitcnt lgkmcnt(0)
	s_barrier
	s_setprio 1
	s_waitcnt lgkmcnt(0)
	v_mfma_f32_16x16x32_bf16 v[62:65], v[146:149], v[200:203], v[62:65]
	v_mfma_f32_16x16x32_bf16 v[58:61], v[164:167], v[200:203], v[58:61]
	v_mfma_f32_16x16x32_bf16 v[54:57], v[146:149], v[208:211], v[54:57]
	v_mfma_f32_16x16x32_bf16 v[50:53], v[164:167], v[208:211], v[50:53]
	v_mfma_f32_16x16x32_bf16 v[46:49], v[146:149], v[216:219], v[46:49]
	v_mfma_f32_16x16x32_bf16 v[42:45], v[164:167], v[216:219], v[42:45]
	v_mfma_f32_16x16x32_bf16 v[38:41], v[146:149], v[224:227], v[38:41]
	v_mfma_f32_16x16x32_bf16 v[34:37], v[164:167], v[224:227], v[34:37]
	v_mfma_f32_16x16x32_bf16 v[62:65], v[150:153], v[204:207], v[62:65]
	v_mfma_f32_16x16x32_bf16 v[58:61], v[172:175], v[204:207], v[58:61]
	v_mfma_f32_16x16x32_bf16 v[54:57], v[150:153], v[212:215], v[54:57]
	v_mfma_f32_16x16x32_bf16 v[50:53], v[172:175], v[212:215], v[50:53]
	v_mfma_f32_16x16x32_bf16 v[46:49], v[150:153], v[220:223], v[46:49]
	v_mfma_f32_16x16x32_bf16 v[42:45], v[172:175], v[220:223], v[42:45]
	v_mfma_f32_16x16x32_bf16 v[38:41], v[150:153], v[228:231], v[38:41]
	v_mfma_f32_16x16x32_bf16 v[34:37], v[172:175], v[228:231], v[34:37]
	s_setprio 0
	s_setprio 1
	v_mfma_f32_16x16x32_bf16 v[30:33], v[176:179], v[200:203], v[30:33]
	v_mfma_f32_16x16x32_bf16 v[26:29], v[184:187], v[200:203], v[26:29]
	v_mfma_f32_16x16x32_bf16 v[22:25], v[176:179], v[208:211], v[22:25]
	v_mfma_f32_16x16x32_bf16 v[18:21], v[184:187], v[208:211], v[18:21]
	v_mfma_f32_16x16x32_bf16 v[14:17], v[176:179], v[216:219], v[14:17]
	v_mfma_f32_16x16x32_bf16 v[10:13], v[184:187], v[216:219], v[10:13]
	v_mfma_f32_16x16x32_bf16 v[6:9], v[176:179], v[224:227], v[6:9]
	v_mfma_f32_16x16x32_bf16 v[2:5], v[184:187], v[224:227], v[2:5]
	v_mfma_f32_16x16x32_bf16 v[30:33], v[180:183], v[204:207], v[30:33]
	v_mfma_f32_16x16x32_bf16 v[26:29], v[188:191], v[204:207], v[26:29]
	v_mfma_f32_16x16x32_bf16 v[22:25], v[180:183], v[212:215], v[22:25]
	v_mfma_f32_16x16x32_bf16 v[18:21], v[188:191], v[212:215], v[18:21]
	v_mfma_f32_16x16x32_bf16 v[14:17], v[180:183], v[220:223], v[14:17]
	v_mfma_f32_16x16x32_bf16 v[10:13], v[188:191], v[220:223], v[10:13]
	v_mfma_f32_16x16x32_bf16 v[6:9], v[180:183], v[228:231], v[6:9]
	v_mfma_f32_16x16x32_bf16 v[2:5], v[188:191], v[228:231], v[2:5]
	s_setprio 0
	s_barrier
	s_add_i32 s96, s96, 2
	s_add_u32 s10, s10, 0x100
	s_addc_u32 s11, s11, 0
	s_cmp_gt_u32 s96, 29
	s_cbranch_scc0 .LBB0_290
	s_and_b64 vcc, exec, s[56:57]
	s_cbranch_vccz .LBB0_293
	s_barrier

.LBB0_473:
	s_add_i32 s16, 0, 0x10000
	s_add_i32 s24, 0, 0x14000
	v_add_u32_e32 v146, s16, v197
	v_add_u32_e32 v182, s24, v197
	ds_read_b128 v[134:137], v146
	ds_read_b128 v[138:141], v146 offset:1024
	ds_read_b128 v[142:145], v146 offset:2048
	ds_read_b128 v[146:149], v146 offset:3072
	ds_read_b128 v[150:153], v182
	ds_read_b128 v[174:177], v182 offset:1024
	ds_read_b128 v[178:181], v182 offset:2048
	ds_read_b128 v[182:185], v182 offset:3072
	ds_read_b128 v[186:189], v200
	ds_read_b128 v[202:205], v200 offset:1024
	ds_read_b128 v[206:209], v200 offset:2048
	ds_read_b128 v[210:213], v200 offset:3072
	ds_read_b128 v[214:217], v200 offset:4096
	ds_read_b128 v[218:221], v200 offset:5120
	ds_read_b128 v[222:225], v200 offset:6144
	ds_read_b128 v[226:229], v200 offset:7168
	s_add_u32 s64, s56, s10
	s_addc_u32 s65, s57, s11
	s_add_u32 s64, s64, 0x100
	s_addc_u32 s65, s65, 0
	s_add_u32 vcc_lo, s93, s10
	s_addc_u32 vcc_hi, s94, s11
	s_cmpk_eq_i32 s10, 0xf00
	s_cselect_b32 s67, s55, s65
	s_cselect_b32 s66, s95, s64
	s_cselect_b32 s65, s53, vcc_hi
	s_cselect_b32 s64, s96, vcc_lo
	v_lshl_add_u64 v[190:191], v[130:131], 0, s[10:11]
	s_add_i32 m0, s80, 0xc000
	s_nop 0
	global_load_lds_dwordx4 v[190:191], off
	v_lshl_add_u64 v[190:191], v[132:133], 0, s[10:11]
	s_add_i32 m0, s80, 0xe000
	s_nop 0
	global_load_lds_dwordx4 v[190:191], off
	s_waitcnt vmcnt(8)
	s_waitcnt lgkmcnt(0)
	s_barrier
	s_setprio 1
	s_waitcnt lgkmcnt(0)
	v_mfma_f32_16x16x32_bf16 v[126:129], v[134:137], v[186:189], v[126:129]
	v_mfma_f32_16x16x32_bf16 v[122:125], v[142:145], v[186:189], v[122:125]
	v_mfma_f32_16x16x32_bf16 v[118:121], v[134:137], v[206:209], v[118:121]
	v_mfma_f32_16x16x32_bf16 v[114:117], v[142:145], v[206:209], v[114:117]
	v_mfma_f32_16x16x32_bf16 v[110:113], v[134:137], v[214:217], v[110:113]
	v_mfma_f32_16x16x32_bf16 v[106:109], v[142:145], v[214:217], v[106:109]
	v_mfma_f32_16x16x32_bf16 v[102:105], v[134:137], v[222:225], v[102:105]
	v_mfma_f32_16x16x32_bf16 v[98:101], v[142:145], v[222:225], v[98:101]
	v_mfma_f32_16x16x32_bf16 v[126:129], v[138:141], v[202:205], v[126:129]
	v_mfma_f32_16x16x32_bf16 v[122:125], v[146:149], v[202:205], v[122:125]
	v_mfma_f32_16x16x32_bf16 v[118:121], v[138:141], v[210:213], v[118:121]
	v_mfma_f32_16x16x32_bf16 v[114:117], v[146:149], v[210:213], v[114:117]
	v_mfma_f32_16x16x32_bf16 v[110:113], v[138:141], v[218:221], v[110:113]
	v_mfma_f32_16x16x32_bf16 v[106:109], v[146:149], v[218:221], v[106:109]
	v_mfma_f32_16x16x32_bf16 v[102:105], v[138:141], v[226:229], v[102:105]
	v_mfma_f32_16x16x32_bf16 v[98:101], v[146:149], v[226:229], v[98:101]
	s_setprio 0
	s_setprio 1
	v_mfma_f32_16x16x32_bf16 v[94:97], v[150:153], v[186:189], v[94:97]
	v_mfma_f32_16x16x32_bf16 v[90:93], v[178:181], v[186:189], v[90:93]
	v_mfma_f32_16x16x32_bf16 v[86:89], v[150:153], v[206:209], v[86:89]
	v_mfma_f32_16x16x32_bf16 v[82:85], v[178:181], v[206:209], v[82:85]
	v_mfma_f32_16x16x32_bf16 v[78:81], v[150:153], v[214:217], v[78:81]
	v_mfma_f32_16x16x32_bf16 v[74:77], v[178:181], v[214:217], v[74:77]
	v_mfma_f32_16x16x32_bf16 v[70:73], v[150:153], v[222:225], v[70:73]
	v_mfma_f32_16x16x32_bf16 v[66:69], v[178:181], v[222:225], v[66:69]
	v_mfma_f32_16x16x32_bf16 v[94:97], v[174:177], v[202:205], v[94:97]
	v_mfma_f32_16x16x32_bf16 v[90:93], v[182:185], v[202:205], v[90:93]
	v_mfma_f32_16x16x32_bf16 v[86:89], v[174:177], v[210:213], v[86:89]
	v_mfma_f32_16x16x32_bf16 v[82:85], v[182:185], v[210:213], v[82:85]
	v_mfma_f32_16x16x32_bf16 v[78:81], v[174:177], v[218:221], v[78:81]
	v_mfma_f32_16x16x32_bf16 v[74:77], v[182:185], v[218:221], v[74:77]
	v_mfma_f32_16x16x32_bf16 v[70:73], v[174:177], v[226:229], v[70:73]
	v_mfma_f32_16x16x32_bf16 v[66:69], v[182:185], v[226:229], v[66:69]
	s_setprio 0
	s_barrier
	s_add_i32 s16, s16, s30
	v_lshl_add_u64 v[190:191], s[64:65], 0, v[154:155]
	s_mov_b32 m0, s16
	ds_read_b128 v[186:189], v200 offset:16384
	ds_read_b128 v[202:205], v200 offset:17408
	ds_read_b128 v[206:209], v200 offset:18432
	ds_read_b128 v[210:213], v200 offset:19456
	ds_read_b128 v[214:217], v200 offset:20480
	ds_read_b128 v[218:221], v200 offset:21504
	ds_read_b128 v[222:225], v200 offset:22528
	ds_read_b128 v[226:229], v200 offset:23552
	global_load_lds_dwordx4 v[190:191], off
	s_add_i32 m0, s16, 0x2000
	s_add_u32 vcc_lo, s64, 0x80000
	v_lshl_add_u64 v[230:231], s[64:65], 0, v[164:165]
	s_addc_u32 vcc_hi, s65, 0
	s_add_i32 s16, s24, s30
	global_load_lds_dwordx4 v[230:231], off
	v_lshl_add_u64 v[232:233], vcc, 0, v[154:155]
	s_mov_b32 m0, s16
	v_lshl_add_u64 v[234:235], s[66:67], 0, v[166:167]
	global_load_lds_dwordx4 v[232:233], off
	v_lshl_add_u64 v[232:233], vcc, 0, v[164:165]
	s_add_i32 m0, s16, 0x2000
	s_nop 0
	global_load_lds_dwordx4 v[232:233], off
	v_lshl_add_u64 v[232:233], s[66:67], 0, v[168:169]
	s_mov_b32 m0, s80
	s_nop 0
	global_load_lds_dwordx4 v[232:233], off
	s_mov_b32 m0, s81
	s_nop 0
	global_load_lds_dwordx4 v[234:235], off
	s_waitcnt vmcnt(8)
	s_waitcnt lgkmcnt(0)
	s_barrier
	s_setprio 1
	s_waitcnt lgkmcnt(0)
	v_mfma_f32_16x16x32_bf16 v[62:65], v[134:137], v[186:189], v[62:65]
	v_mfma_f32_16x16x32_bf16 v[58:61], v[142:145], v[186:189], v[58:61]
	v_mfma_f32_16x16x32_bf16 v[54:57], v[134:137], v[206:209], v[54:57]
	v_mfma_f32_16x16x32_bf16 v[50:53], v[142:145], v[206:209], v[50:53]
	v_mfma_f32_16x16x32_bf16 v[46:49], v[134:137], v[214:217], v[46:49]
	v_mfma_f32_16x16x32_bf16 v[42:45], v[142:145], v[214:217], v[42:45]
	v_mfma_f32_16x16x32_bf16 v[38:41], v[134:137], v[222:225], v[38:41]
	v_mfma_f32_16x16x32_bf16 v[34:37], v[142:145], v[222:225], v[34:37]
	v_mfma_f32_16x16x32_bf16 v[62:65], v[138:141], v[202:205], v[62:65]
	v_mfma_f32_16x16x32_bf16 v[58:61], v[146:149], v[202:205], v[58:61]
	v_mfma_f32_16x16x32_bf16 v[54:57], v[138:141], v[210:213], v[54:57]
	v_mfma_f32_16x16x32_bf16 v[50:53], v[146:149], v[210:213], v[50:53]
	v_mfma_f32_16x16x32_bf16 v[46:49], v[138:141], v[218:221], v[46:49]
	v_mfma_f32_16x16x32_bf16 v[42:45], v[146:149], v[218:221], v[42:45]
	v_mfma_f32_16x16x32_bf16 v[38:41], v[138:141], v[226:229], v[38:41]
	v_mfma_f32_16x16x32_bf16 v[34:37], v[146:149], v[226:229], v[34:37]
	s_setprio 0
	s_setprio 1
	v_mfma_f32_16x16x32_bf16 v[30:33], v[150:153], v[186:189], v[30:33]
	v_mfma_f32_16x16x32_bf16 v[26:29], v[178:181], v[186:189], v[26:29]
	v_mfma_f32_16x16x32_bf16 v[22:25], v[150:153], v[206:209], v[22:25]
	v_mfma_f32_16x16x32_bf16 v[18:21], v[178:181], v[206:209], v[18:21]
	v_mfma_f32_16x16x32_bf16 v[14:17], v[150:153], v[214:217], v[14:17]
	v_mfma_f32_16x16x32_bf16 v[10:13], v[178:181], v[214:217], v[10:13]
	v_mfma_f32_16x16x32_bf16 v[6:9], v[150:153], v[222:225], v[6:9]
	v_mfma_f32_16x16x32_bf16 v[2:5], v[178:181], v[222:225], v[2:5]
	v_mfma_f32_16x16x32_bf16 v[30:33], v[174:177], v[202:205], v[30:33]
	v_mfma_f32_16x16x32_bf16 v[26:29], v[182:185], v[202:205], v[26:29]
	v_mfma_f32_16x16x32_bf16 v[22:25], v[174:177], v[210:213], v[22:25]
	v_mfma_f32_16x16x32_bf16 v[18:21], v[182:185], v[210:213], v[18:21]
	v_mfma_f32_16x16x32_bf16 v[14:17], v[174:177], v[218:221], v[14:17]
	v_mfma_f32_16x16x32_bf16 v[10:13], v[182:185], v[218:221], v[10:13]
	v_mfma_f32_16x16x32_bf16 v[6:9], v[174:177], v[226:229], v[6:9]
	v_mfma_f32_16x16x32_bf16 v[2:5], v[182:185], v[226:229], v[2:5]
	s_setprio 0
	s_barrier
	s_add_i32 s16, 0, 0x18000
	s_add_i32 s24, 0, 0x1c000
	v_add_u32_e32 v146, s16, v197
	v_add_u32_e32 v182, s24, v197
	ds_read_b128 v[134:137], v146
	ds_read_b128 v[138:141], v146 offset:1024
	ds_read_b128 v[142:145], v146 offset:2048
	ds_read_b128 v[146:149], v146 offset:3072
	ds_read_b128 v[150:153], v182
	ds_read_b128 v[174:177], v182 offset:1024
	ds_read_b128 v[178:181], v182 offset:2048
	ds_read_b128 v[182:185], v182 offset:3072
	s_add_u32 s66, s66, 0x80000
	s_addc_u32 s67, s67, 0
	s_mov_b32 m0, s82
	v_lshl_add_u64 v[236:237], s[66:67], 0, v[168:169]
	ds_read_b128 v[186:189], v200 offset:32768
	ds_read_b128 v[202:205], v200 offset:33792
	ds_read_b128 v[206:209], v200 offset:34816
	ds_read_b128 v[210:213], v200 offset:35840
	ds_read_b128 v[214:217], v200 offset:36864
	ds_read_b128 v[218:221], v200 offset:37888
	ds_read_b128 v[222:225], v200 offset:38912
	ds_read_b128 v[226:229], v200 offset:39936
	global_load_lds_dwordx4 v[236:237], off
	v_lshl_add_u64 v[236:237], s[66:67], 0, v[166:167]
	s_mov_b32 m0, s83
	s_nop 0
	global_load_lds_dwordx4 v[236:237], off
	s_waitcnt vmcnt(8)
	s_waitcnt lgkmcnt(0)
	s_barrier
	s_setprio 1
	s_waitcnt lgkmcnt(0)
	v_mfma_f32_16x16x32_bf16 v[126:129], v[134:137], v[186:189], v[126:129]
	v_mfma_f32_16x16x32_bf16 v[122:125], v[142:145], v[186:189], v[122:125]
	v_mfma_f32_16x16x32_bf16 v[118:121], v[134:137], v[206:209], v[118:121]
	v_mfma_f32_16x16x32_bf16 v[114:117], v[142:145], v[206:209], v[114:117]
	v_mfma_f32_16x16x32_bf16 v[110:113], v[134:137], v[214:217], v[110:113]
	v_mfma_f32_16x16x32_bf16 v[106:109], v[142:145], v[214:217], v[106:109]
	v_mfma_f32_16x16x32_bf16 v[102:105], v[134:137], v[222:225], v[102:105]
	v_mfma_f32_16x16x32_bf16 v[98:101], v[142:145], v[222:225], v[98:101]
	v_mfma_f32_16x16x32_bf16 v[126:129], v[138:141], v[202:205], v[126:129]
	v_mfma_f32_16x16x32_bf16 v[122:125], v[146:149], v[202:205], v[122:125]
	v_mfma_f32_16x16x32_bf16 v[118:121], v[138:141], v[210:213], v[118:121]
	v_mfma_f32_16x16x32_bf16 v[114:117], v[146:149], v[210:213], v[114:117]
	v_mfma_f32_16x16x32_bf16 v[110:113], v[138:141], v[218:221], v[110:113]
	v_mfma_f32_16x16x32_bf16 v[106:109], v[146:149], v[218:221], v[106:109]
	v_mfma_f32_16x16x32_bf16 v[102:105], v[138:141], v[226:229], v[102:105]
	v_mfma_f32_16x16x32_bf16 v[98:101], v[146:149], v[226:229], v[98:101]
	s_setprio 0
	s_setprio 1
	v_mfma_f32_16x16x32_bf16 v[94:97], v[150:153], v[186:189], v[94:97]
	v_mfma_f32_16x16x32_bf16 v[90:93], v[178:181], v[186:189], v[90:93]
	v_mfma_f32_16x16x32_bf16 v[86:89], v[150:153], v[206:209], v[86:89]
	v_mfma_f32_16x16x32_bf16 v[82:85], v[178:181], v[206:209], v[82:85]
	v_mfma_f32_16x16x32_bf16 v[78:81], v[150:153], v[214:217], v[78:81]
	v_mfma_f32_16x16x32_bf16 v[74:77], v[178:181], v[214:217], v[74:77]
	v_mfma_f32_16x16x32_bf16 v[70:73], v[150:153], v[222:225], v[70:73]
	v_mfma_f32_16x16x32_bf16 v[66:69], v[178:181], v[222:225], v[66:69]
	v_mfma_f32_16x16x32_bf16 v[94:97], v[174:177], v[202:205], v[94:97]
	v_mfma_f32_16x16x32_bf16 v[90:93], v[182:185], v[202:205], v[90:93]
	v_mfma_f32_16x16x32_bf16 v[86:89], v[174:177], v[210:213], v[86:89]
	v_mfma_f32_16x16x32_bf16 v[82:85], v[182:185], v[210:213], v[82:85]
	v_mfma_f32_16x16x32_bf16 v[78:81], v[174:177], v[218:221], v[78:81]
	v_mfma_f32_16x16x32_bf16 v[74:77], v[182:185], v[218:221], v[74:77]
	v_mfma_f32_16x16x32_bf16 v[70:73], v[174:177], v[226:229], v[70:73]
	v_mfma_f32_16x16x32_bf16 v[66:69], v[182:185], v[226:229], v[66:69]
	s_setprio 0
	s_barrier
	s_add_i32 s16, s16, s30
	v_lshl_add_u64 v[190:191], v[190:191], 0, s[34:35]
	s_mov_b32 m0, s16
	ds_read_b128 v[186:189], v200 offset:49152
	ds_read_b128 v[202:205], v200 offset:50176
	ds_read_b128 v[206:209], v200 offset:51200
	ds_read_b128 v[210:213], v200 offset:52224
	ds_read_b128 v[214:217], v200 offset:53248
	ds_read_b128 v[218:221], v200 offset:54272
	ds_read_b128 v[222:225], v200 offset:55296
	ds_read_b128 v[226:229], v200 offset:56320
	global_load_lds_dwordx4 v[190:191], off
	s_add_i32 m0, s16, 0x2000
	s_add_u32 s64, s64, 0x80080
	v_lshl_add_u64 v[190:191], v[230:231], 0, s[34:35]
	s_addc_u32 s65, s65, 0
	s_add_i32 s16, s24, s30
	global_load_lds_dwordx4 v[190:191], off
	v_lshl_add_u64 v[190:191], s[64:65], 0, v[154:155]
	s_mov_b32 m0, s16
	s_nop 0
	global_load_lds_dwordx4 v[190:191], off
	v_lshl_add_u64 v[190:191], s[64:65], 0, v[164:165]
	s_add_i32 m0, s16, 0x2000
	s_nop 0
	global_load_lds_dwordx4 v[190:191], off
	v_lshl_add_u64 v[190:191], v[232:233], 0, s[34:35]
	s_mov_b32 m0, s84
	s_nop 0
	global_load_lds_dwordx4 v[190:191], off
	v_lshl_add_u64 v[190:191], v[234:235], 0, s[34:35]
	s_mov_b32 m0, s85
	s_nop 0
	global_load_lds_dwordx4 v[190:191], off
	s_waitcnt vmcnt(8)
	s_waitcnt lgkmcnt(0)
	s_barrier
	s_setprio 1
	s_waitcnt lgkmcnt(0)
	v_mfma_f32_16x16x32_bf16 v[62:65], v[134:137], v[186:189], v[62:65]
	v_mfma_f32_16x16x32_bf16 v[58:61], v[142:145], v[186:189], v[58:61]
	v_mfma_f32_16x16x32_bf16 v[54:57], v[134:137], v[206:209], v[54:57]
	v_mfma_f32_16x16x32_bf16 v[50:53], v[142:145], v[206:209], v[50:53]
	v_mfma_f32_16x16x32_bf16 v[46:49], v[134:137], v[214:217], v[46:49]
	v_mfma_f32_16x16x32_bf16 v[42:45], v[142:145], v[214:217], v[42:45]
	v_mfma_f32_16x16x32_bf16 v[38:41], v[134:137], v[222:225], v[38:41]
	v_mfma_f32_16x16x32_bf16 v[34:37], v[142:145], v[222:225], v[34:37]
	v_mfma_f32_16x16x32_bf16 v[62:65], v[138:141], v[202:205], v[62:65]
	v_mfma_f32_16x16x32_bf16 v[58:61], v[146:149], v[202:205], v[58:61]
	v_mfma_f32_16x16x32_bf16 v[54:57], v[138:141], v[210:213], v[54:57]
	v_mfma_f32_16x16x32_bf16 v[50:53], v[146:149], v[210:213], v[50:53]
	v_mfma_f32_16x16x32_bf16 v[46:49], v[138:141], v[218:221], v[46:49]
	v_mfma_f32_16x16x32_bf16 v[42:45], v[146:149], v[218:221], v[42:45]
	v_mfma_f32_16x16x32_bf16 v[38:41], v[138:141], v[226:229], v[38:41]
	v_mfma_f32_16x16x32_bf16 v[34:37], v[146:149], v[226:229], v[34:37]
	s_setprio 0
	s_setprio 1
	v_mfma_f32_16x16x32_bf16 v[30:33], v[150:153], v[186:189], v[30:33]
	v_mfma_f32_16x16x32_bf16 v[26:29], v[178:181], v[186:189], v[26:29]
	v_mfma_f32_16x16x32_bf16 v[22:25], v[150:153], v[206:209], v[22:25]
	v_mfma_f32_16x16x32_bf16 v[18:21], v[178:181], v[206:209], v[18:21]
	v_mfma_f32_16x16x32_bf16 v[14:17], v[150:153], v[214:217], v[14:17]
	v_mfma_f32_16x16x32_bf16 v[10:13], v[178:181], v[214:217], v[10:13]
	v_mfma_f32_16x16x32_bf16 v[6:9], v[150:153], v[222:225], v[6:9]
	v_mfma_f32_16x16x32_bf16 v[2:5], v[178:181], v[222:225], v[2:5]
	v_mfma_f32_16x16x32_bf16 v[30:33], v[174:177], v[202:205], v[30:33]
	v_mfma_f32_16x16x32_bf16 v[26:29], v[182:185], v[202:205], v[26:29]
	v_mfma_f32_16x16x32_bf16 v[22:25], v[174:177], v[210:213], v[22:25]
	v_mfma_f32_16x16x32_bf16 v[18:21], v[182:185], v[210:213], v[18:21]
	v_mfma_f32_16x16x32_bf16 v[14:17], v[174:177], v[218:221], v[14:17]
	v_mfma_f32_16x16x32_bf16 v[10:13], v[182:185], v[218:221], v[10:13]
	v_mfma_f32_16x16x32_bf16 v[6:9], v[174:177], v[226:229], v[6:9]
	v_mfma_f32_16x16x32_bf16 v[2:5], v[182:185], v[226:229], v[2:5]
	s_setprio 0
	s_barrier
	s_add_i32 s97, s97, 2
	s_add_u32 s10, s10, 0x100
	s_addc_u32 s11, s11, 0
	s_cmp_gt_u32 s97, 29
	s_cbranch_scc0 .LBB0_473
	s_and_b64 vcc, exec, s[46:47]
	s_cbranch_vccz .LBB0_476
	s_barrier

.LBB0_623:
	s_add_i32 s79, 0, 0x10000
	s_add_i32 s55, 0, 0x14000
	v_add_u32_e32 v148, s79, v204
	v_add_u32_e32 v186, s55, v204
	ds_read_b128 v[136:139], v148
	ds_read_b128 v[140:143], v148 offset:1024
	ds_read_b128 v[144:147], v148 offset:2048
	ds_read_b128 v[148:151], v148 offset:3072
	ds_read_b128 v[152:155], v186
	ds_read_b128 v[156:159], v186 offset:1024
	ds_read_b128 v[160:163], v186 offset:2048
	ds_read_b128 v[186:189], v186 offset:3072
	ds_read_b128 v[190:193], v205
	ds_read_b128 v[194:197], v205 offset:1024
	ds_read_b128 v[206:209], v205 offset:2048
	ds_read_b128 v[210:213], v205 offset:3072
	ds_read_b128 v[214:217], v205 offset:4096
	ds_read_b128 v[218:221], v205 offset:5120
	ds_read_b128 v[222:225], v205 offset:6144
	ds_read_b128 v[226:229], v205 offset:7168
	s_add_u32 s8, s52, s0
	s_addc_u32 s9, s53, s1
	s_add_u32 s8, s8, 0x100
	s_addc_u32 s9, s9, 0
	s_add_u32 s101, s76, s0
	s_addc_u32 s78, s77, s1
	s_cmpk_eq_i32 s0, 0xf00
	s_cselect_b32 s11, s12, s9
	s_cselect_b32 s10, s13, s8
	s_cselect_b32 s9, s26, s78
	s_cselect_b32 s8, s27, s101
	v_lshl_add_u64 v[230:231], v[132:133], 0, s[0:1]
	s_add_i32 m0, s25, 0xc000
	s_nop 0
	global_load_lds_dwordx4 v[230:231], off
	v_lshl_add_u64 v[230:231], v[134:135], 0, s[0:1]
	s_add_i32 m0, s25, 0xe000
	s_nop 0
	global_load_lds_dwordx4 v[230:231], off
	s_waitcnt vmcnt(8)
	s_waitcnt lgkmcnt(0)
	s_barrier
	s_setprio 1
	s_waitcnt lgkmcnt(0)
	v_mfma_f32_16x16x32_bf16 v[128:131], v[136:139], v[190:193], v[128:131]
	v_mfma_f32_16x16x32_bf16 v[124:127], v[144:147], v[190:193], v[124:127]
	v_mfma_f32_16x16x32_bf16 v[120:123], v[136:139], v[206:209], v[120:123]
	v_mfma_f32_16x16x32_bf16 v[116:119], v[144:147], v[206:209], v[116:119]
	v_mfma_f32_16x16x32_bf16 v[112:115], v[136:139], v[214:217], v[112:115]
	v_mfma_f32_16x16x32_bf16 v[108:111], v[144:147], v[214:217], v[108:111]
	v_mfma_f32_16x16x32_bf16 v[104:107], v[136:139], v[222:225], v[104:107]
	v_mfma_f32_16x16x32_bf16 v[100:103], v[144:147], v[222:225], v[100:103]
	v_mfma_f32_16x16x32_bf16 v[128:131], v[140:143], v[194:197], v[128:131]
	v_mfma_f32_16x16x32_bf16 v[124:127], v[148:151], v[194:197], v[124:127]
	v_mfma_f32_16x16x32_bf16 v[120:123], v[140:143], v[210:213], v[120:123]
	v_mfma_f32_16x16x32_bf16 v[116:119], v[148:151], v[210:213], v[116:119]
	v_mfma_f32_16x16x32_bf16 v[112:115], v[140:143], v[218:221], v[112:115]
	v_mfma_f32_16x16x32_bf16 v[108:111], v[148:151], v[218:221], v[108:111]
	v_mfma_f32_16x16x32_bf16 v[104:107], v[140:143], v[226:229], v[104:107]
	v_mfma_f32_16x16x32_bf16 v[100:103], v[148:151], v[226:229], v[100:103]
	s_setprio 0
	s_setprio 1
	v_mfma_f32_16x16x32_bf16 v[96:99], v[152:155], v[190:193], v[96:99]
	v_mfma_f32_16x16x32_bf16 v[92:95], v[160:163], v[190:193], v[92:95]
	v_mfma_f32_16x16x32_bf16 v[88:91], v[152:155], v[206:209], v[88:91]
	v_mfma_f32_16x16x32_bf16 v[84:87], v[160:163], v[206:209], v[84:87]
	v_mfma_f32_16x16x32_bf16 v[80:83], v[152:155], v[214:217], v[80:83]
	v_mfma_f32_16x16x32_bf16 v[76:79], v[160:163], v[214:217], v[76:79]
	v_mfma_f32_16x16x32_bf16 v[72:75], v[152:155], v[222:225], v[72:75]
	v_mfma_f32_16x16x32_bf16 v[68:71], v[160:163], v[222:225], v[68:71]
	v_mfma_f32_16x16x32_bf16 v[96:99], v[156:159], v[194:197], v[96:99]
	v_mfma_f32_16x16x32_bf16 v[92:95], v[186:189], v[194:197], v[92:95]
	v_mfma_f32_16x16x32_bf16 v[88:91], v[156:159], v[210:213], v[88:91]
	v_mfma_f32_16x16x32_bf16 v[84:87], v[186:189], v[210:213], v[84:87]
	v_mfma_f32_16x16x32_bf16 v[80:83], v[156:159], v[218:221], v[80:83]
	v_mfma_f32_16x16x32_bf16 v[76:79], v[186:189], v[218:221], v[76:79]
	v_mfma_f32_16x16x32_bf16 v[72:75], v[156:159], v[226:229], v[72:75]
	v_mfma_f32_16x16x32_bf16 v[68:71], v[186:189], v[226:229], v[68:71]
	s_setprio 0
	s_barrier
	s_add_i32 s78, s79, s24
	v_lshl_add_u64 v[230:231], s[8:9], 0, v[170:171]
	s_mov_b32 m0, s78
	ds_read_b128 v[190:193], v205 offset:16384
	ds_read_b128 v[194:197], v205 offset:17408
	ds_read_b128 v[206:209], v205 offset:18432
	ds_read_b128 v[210:213], v205 offset:19456
	ds_read_b128 v[214:217], v205 offset:20480
	ds_read_b128 v[218:221], v205 offset:21504
	ds_read_b128 v[222:225], v205 offset:22528
	ds_read_b128 v[226:229], v205 offset:23552
	global_load_lds_dwordx4 v[230:231], off
	s_add_i32 m0, s78, 0x2000
	s_add_u32 s78, s8, 0x80000
	v_lshl_add_u64 v[232:233], s[8:9], 0, v[174:175]
	s_addc_u32 s79, s9, 0
	s_add_i32 s55, s55, s24
	global_load_lds_dwordx4 v[232:233], off
	v_lshl_add_u64 v[234:235], s[78:79], 0, v[170:171]
	s_mov_b32 m0, s55
	v_lshl_add_u64 v[236:237], s[10:11], 0, v[172:173]
	global_load_lds_dwordx4 v[234:235], off
	v_lshl_add_u64 v[234:235], s[78:79], 0, v[174:175]
	s_add_i32 m0, s55, 0x2000
	s_nop 0
	global_load_lds_dwordx4 v[234:235], off
	v_lshl_add_u64 v[234:235], s[10:11], 0, v[168:169]
	s_mov_b32 m0, s25
	s_nop 0
	global_load_lds_dwordx4 v[234:235], off
	s_mov_b32 m0, s30
	s_nop 0
	global_load_lds_dwordx4 v[236:237], off
	s_waitcnt vmcnt(8)
	s_waitcnt lgkmcnt(0)
	s_barrier
	s_setprio 1
	s_waitcnt lgkmcnt(0)
	v_mfma_f32_16x16x32_bf16 v[64:67], v[136:139], v[190:193], v[64:67]
	v_mfma_f32_16x16x32_bf16 v[60:63], v[144:147], v[190:193], v[60:63]
	v_mfma_f32_16x16x32_bf16 v[56:59], v[136:139], v[206:209], v[56:59]
	v_mfma_f32_16x16x32_bf16 v[52:55], v[144:147], v[206:209], v[52:55]
	v_mfma_f32_16x16x32_bf16 v[48:51], v[136:139], v[214:217], v[48:51]
	v_mfma_f32_16x16x32_bf16 v[44:47], v[144:147], v[214:217], v[44:47]
	v_mfma_f32_16x16x32_bf16 v[40:43], v[136:139], v[222:225], v[40:43]
	v_mfma_f32_16x16x32_bf16 v[36:39], v[144:147], v[222:225], v[36:39]
	v_mfma_f32_16x16x32_bf16 v[64:67], v[140:143], v[194:197], v[64:67]
	v_mfma_f32_16x16x32_bf16 v[60:63], v[148:151], v[194:197], v[60:63]
	v_mfma_f32_16x16x32_bf16 v[56:59], v[140:143], v[210:213], v[56:59]
	v_mfma_f32_16x16x32_bf16 v[52:55], v[148:151], v[210:213], v[52:55]
	v_mfma_f32_16x16x32_bf16 v[48:51], v[140:143], v[218:221], v[48:51]
	v_mfma_f32_16x16x32_bf16 v[44:47], v[148:151], v[218:221], v[44:47]
	v_mfma_f32_16x16x32_bf16 v[40:43], v[140:143], v[226:229], v[40:43]
	v_mfma_f32_16x16x32_bf16 v[36:39], v[148:151], v[226:229], v[36:39]
	s_setprio 0
	s_setprio 1
	v_mfma_f32_16x16x32_bf16 v[32:35], v[152:155], v[190:193], v[32:35]
	v_mfma_f32_16x16x32_bf16 v[28:31], v[160:163], v[190:193], v[28:31]
	v_mfma_f32_16x16x32_bf16 v[24:27], v[152:155], v[206:209], v[24:27]
	v_mfma_f32_16x16x32_bf16 v[20:23], v[160:163], v[206:209], v[20:23]
	v_mfma_f32_16x16x32_bf16 v[16:19], v[152:155], v[214:217], v[16:19]
	v_mfma_f32_16x16x32_bf16 v[12:15], v[160:163], v[214:217], v[12:15]
	v_mfma_f32_16x16x32_bf16 v[8:11], v[152:155], v[222:225], v[8:11]
	v_mfma_f32_16x16x32_bf16 v[4:7], v[160:163], v[222:225], v[4:7]
	v_mfma_f32_16x16x32_bf16 v[32:35], v[156:159], v[194:197], v[32:35]
	v_mfma_f32_16x16x32_bf16 v[28:31], v[186:189], v[194:197], v[28:31]
	v_mfma_f32_16x16x32_bf16 v[24:27], v[156:159], v[210:213], v[24:27]
	v_mfma_f32_16x16x32_bf16 v[20:23], v[186:189], v[210:213], v[20:23]
	v_mfma_f32_16x16x32_bf16 v[16:19], v[156:159], v[218:221], v[16:19]
	v_mfma_f32_16x16x32_bf16 v[12:15], v[186:189], v[218:221], v[12:15]
	v_mfma_f32_16x16x32_bf16 v[8:11], v[156:159], v[226:229], v[8:11]
	v_mfma_f32_16x16x32_bf16 v[4:7], v[186:189], v[226:229], v[4:7]
	s_setprio 0
	s_barrier
	s_add_i32 s55, 0, 0x18000
	s_add_i32 s78, 0, 0x1c000
	v_add_u32_e32 v148, s55, v204
	v_add_u32_e32 v186, s78, v204
	ds_read_b128 v[136:139], v148
	ds_read_b128 v[140:143], v148 offset:1024
	ds_read_b128 v[144:147], v148 offset:2048
	ds_read_b128 v[148:151], v148 offset:3072
	ds_read_b128 v[152:155], v186
	ds_read_b128 v[156:159], v186 offset:1024
	ds_read_b128 v[160:163], v186 offset:2048
	ds_read_b128 v[186:189], v186 offset:3072
	s_add_u32 s10, s10, 0x80000
	s_addc_u32 s11, s11, 0
	s_mov_b32 m0, s31
	v_lshl_add_u64 v[238:239], s[10:11], 0, v[168:169]
	ds_read_b128 v[190:193], v205 offset:32768
	ds_read_b128 v[194:197], v205 offset:33792
	ds_read_b128 v[206:209], v205 offset:34816
	ds_read_b128 v[210:213], v205 offset:35840
	ds_read_b128 v[214:217], v205 offset:36864
	ds_read_b128 v[218:221], v205 offset:37888
	ds_read_b128 v[222:225], v205 offset:38912
	ds_read_b128 v[226:229], v205 offset:39936
	global_load_lds_dwordx4 v[238:239], off
	v_lshl_add_u64 v[238:239], s[10:11], 0, v[172:173]
	s_mov_b32 m0, s36
	s_nop 0
	global_load_lds_dwordx4 v[238:239], off
	s_waitcnt vmcnt(8)
	s_waitcnt lgkmcnt(0)
	s_barrier
	s_setprio 1
	s_waitcnt lgkmcnt(0)
	v_mfma_f32_16x16x32_bf16 v[128:131], v[136:139], v[190:193], v[128:131]
	v_mfma_f32_16x16x32_bf16 v[124:127], v[144:147], v[190:193], v[124:127]
	v_mfma_f32_16x16x32_bf16 v[120:123], v[136:139], v[206:209], v[120:123]
	v_mfma_f32_16x16x32_bf16 v[116:119], v[144:147], v[206:209], v[116:119]
	v_mfma_f32_16x16x32_bf16 v[112:115], v[136:139], v[214:217], v[112:115]
	v_mfma_f32_16x16x32_bf16 v[108:111], v[144:147], v[214:217], v[108:111]
	v_mfma_f32_16x16x32_bf16 v[104:107], v[136:139], v[222:225], v[104:107]
	v_mfma_f32_16x16x32_bf16 v[100:103], v[144:147], v[222:225], v[100:103]
	v_mfma_f32_16x16x32_bf16 v[128:131], v[140:143], v[194:197], v[128:131]
	v_mfma_f32_16x16x32_bf16 v[124:127], v[148:151], v[194:197], v[124:127]
	v_mfma_f32_16x16x32_bf16 v[120:123], v[140:143], v[210:213], v[120:123]
	v_mfma_f32_16x16x32_bf16 v[116:119], v[148:151], v[210:213], v[116:119]
	v_mfma_f32_16x16x32_bf16 v[112:115], v[140:143], v[218:221], v[112:115]
	v_mfma_f32_16x16x32_bf16 v[108:111], v[148:151], v[218:221], v[108:111]
	v_mfma_f32_16x16x32_bf16 v[104:107], v[140:143], v[226:229], v[104:107]
	v_mfma_f32_16x16x32_bf16 v[100:103], v[148:151], v[226:229], v[100:103]
	s_setprio 0
	s_setprio 1
	v_mfma_f32_16x16x32_bf16 v[96:99], v[152:155], v[190:193], v[96:99]
	v_mfma_f32_16x16x32_bf16 v[92:95], v[160:163], v[190:193], v[92:95]
	v_mfma_f32_16x16x32_bf16 v[88:91], v[152:155], v[206:209], v[88:91]
	v_mfma_f32_16x16x32_bf16 v[84:87], v[160:163], v[206:209], v[84:87]
	v_mfma_f32_16x16x32_bf16 v[80:83], v[152:155], v[214:217], v[80:83]
	v_mfma_f32_16x16x32_bf16 v[76:79], v[160:163], v[214:217], v[76:79]
	v_mfma_f32_16x16x32_bf16 v[72:75], v[152:155], v[222:225], v[72:75]
	v_mfma_f32_16x16x32_bf16 v[68:71], v[160:163], v[222:225], v[68:71]
	v_mfma_f32_16x16x32_bf16 v[96:99], v[156:159], v[194:197], v[96:99]
	v_mfma_f32_16x16x32_bf16 v[92:95], v[186:189], v[194:197], v[92:95]
	v_mfma_f32_16x16x32_bf16 v[88:91], v[156:159], v[210:213], v[88:91]
	v_mfma_f32_16x16x32_bf16 v[84:87], v[186:189], v[210:213], v[84:87]
	v_mfma_f32_16x16x32_bf16 v[80:83], v[156:159], v[218:221], v[80:83]
	v_mfma_f32_16x16x32_bf16 v[76:79], v[186:189], v[218:221], v[76:79]
	v_mfma_f32_16x16x32_bf16 v[72:75], v[156:159], v[226:229], v[72:75]
	v_mfma_f32_16x16x32_bf16 v[68:71], v[186:189], v[226:229], v[68:71]
	s_setprio 0
	s_barrier
	s_add_i32 s10, s55, s24
	v_lshl_add_u64 v[230:231], v[230:231], 0, s[28:29]
	s_mov_b32 m0, s10
	ds_read_b128 v[190:193], v205 offset:49152
	ds_read_b128 v[194:197], v205 offset:50176
	ds_read_b128 v[206:209], v205 offset:51200
	ds_read_b128 v[210:213], v205 offset:52224
	ds_read_b128 v[214:217], v205 offset:53248
	ds_read_b128 v[218:221], v205 offset:54272
	ds_read_b128 v[222:225], v205 offset:55296
	ds_read_b128 v[226:229], v205 offset:56320
	global_load_lds_dwordx4 v[230:231], off
	s_add_i32 m0, s10, 0x2000
	s_add_u32 s8, s8, 0x80080
	v_lshl_add_u64 v[230:231], v[232:233], 0, s[28:29]
	s_addc_u32 s9, s9, 0
	s_add_i32 s10, s78, s24
	global_load_lds_dwordx4 v[230:231], off
	v_lshl_add_u64 v[230:231], s[8:9], 0, v[170:171]
	s_mov_b32 m0, s10
	s_nop 0
	global_load_lds_dwordx4 v[230:231], off
	v_lshl_add_u64 v[230:231], s[8:9], 0, v[174:175]
	s_add_i32 m0, s10, 0x2000
	s_nop 0
	global_load_lds_dwordx4 v[230:231], off
	v_lshl_add_u64 v[230:231], v[234:235], 0, s[28:29]
	s_mov_b32 m0, s45
	s_nop 0
	global_load_lds_dwordx4 v[230:231], off
	v_lshl_add_u64 v[230:231], v[236:237], 0, s[28:29]
	s_mov_b32 m0, s60
	s_nop 0
	global_load_lds_dwordx4 v[230:231], off
	s_waitcnt vmcnt(8)
	s_waitcnt lgkmcnt(0)
	s_barrier
	s_setprio 1
	s_waitcnt lgkmcnt(0)
	v_mfma_f32_16x16x32_bf16 v[64:67], v[136:139], v[190:193], v[64:67]
	v_mfma_f32_16x16x32_bf16 v[60:63], v[144:147], v[190:193], v[60:63]
	v_mfma_f32_16x16x32_bf16 v[56:59], v[136:139], v[206:209], v[56:59]
	v_mfma_f32_16x16x32_bf16 v[52:55], v[144:147], v[206:209], v[52:55]
	v_mfma_f32_16x16x32_bf16 v[48:51], v[136:139], v[214:217], v[48:51]
	v_mfma_f32_16x16x32_bf16 v[44:47], v[144:147], v[214:217], v[44:47]
	v_mfma_f32_16x16x32_bf16 v[40:43], v[136:139], v[222:225], v[40:43]
	v_mfma_f32_16x16x32_bf16 v[36:39], v[144:147], v[222:225], v[36:39]
	v_mfma_f32_16x16x32_bf16 v[64:67], v[140:143], v[194:197], v[64:67]
	v_mfma_f32_16x16x32_bf16 v[60:63], v[148:151], v[194:197], v[60:63]
	v_mfma_f32_16x16x32_bf16 v[56:59], v[140:143], v[210:213], v[56:59]
	v_mfma_f32_16x16x32_bf16 v[52:55], v[148:151], v[210:213], v[52:55]
	v_mfma_f32_16x16x32_bf16 v[48:51], v[140:143], v[218:221], v[48:51]
	v_mfma_f32_16x16x32_bf16 v[44:47], v[148:151], v[218:221], v[44:47]
	v_mfma_f32_16x16x32_bf16 v[40:43], v[140:143], v[226:229], v[40:43]
	v_mfma_f32_16x16x32_bf16 v[36:39], v[148:151], v[226:229], v[36:39]
	s_setprio 0
	s_setprio 1
	v_mfma_f32_16x16x32_bf16 v[32:35], v[152:155], v[190:193], v[32:35]
	v_mfma_f32_16x16x32_bf16 v[28:31], v[160:163], v[190:193], v[28:31]
	v_mfma_f32_16x16x32_bf16 v[24:27], v[152:155], v[206:209], v[24:27]
	v_mfma_f32_16x16x32_bf16 v[20:23], v[160:163], v[206:209], v[20:23]
	v_mfma_f32_16x16x32_bf16 v[16:19], v[152:155], v[214:217], v[16:19]
	v_mfma_f32_16x16x32_bf16 v[12:15], v[160:163], v[214:217], v[12:15]
	v_mfma_f32_16x16x32_bf16 v[8:11], v[152:155], v[222:225], v[8:11]
	v_mfma_f32_16x16x32_bf16 v[4:7], v[160:163], v[222:225], v[4:7]
	v_mfma_f32_16x16x32_bf16 v[32:35], v[156:159], v[194:197], v[32:35]
	v_mfma_f32_16x16x32_bf16 v[28:31], v[186:189], v[194:197], v[28:31]
	v_mfma_f32_16x16x32_bf16 v[24:27], v[156:159], v[210:213], v[24:27]
	v_mfma_f32_16x16x32_bf16 v[20:23], v[186:189], v[210:213], v[20:23]
	v_mfma_f32_16x16x32_bf16 v[16:19], v[156:159], v[218:221], v[16:19]
	v_mfma_f32_16x16x32_bf16 v[12:15], v[186:189], v[218:221], v[12:15]
	v_mfma_f32_16x16x32_bf16 v[8:11], v[156:159], v[226:229], v[8:11]
	v_mfma_f32_16x16x32_bf16 v[4:7], v[186:189], v[226:229], v[4:7]
	s_setprio 0
	s_barrier
	s_add_i32 s43, s43, 2
	s_add_u32 s0, s0, 0x100
	s_addc_u32 s1, s1, 0
	s_cmp_gt_u32 s43, 29
	s_cbranch_scc0 .LBB0_623
	s_and_b64 vcc, exec, s[50:51]
	s_cbranch_vccz .LBB0_626
	s_barrier

.LBB0_866:
	s_add_i32 s75, 0, 0x10000
	s_add_i32 s67, 0, 0x14000
	v_add_u32_e32 v148, s75, v189
	v_add_u32_e32 v178, s67, v189
	ds_read_b128 v[136:139], v148
	ds_read_b128 v[140:143], v148 offset:1024
	ds_read_b128 v[144:147], v148 offset:2048
	ds_read_b128 v[148:151], v148 offset:3072
	ds_read_b128 v[152:155], v178
	ds_read_b128 v[170:173], v178 offset:1024
	ds_read_b128 v[174:177], v178 offset:2048
	ds_read_b128 v[178:181], v178 offset:3072
	ds_read_b128 v[182:185], v191
	ds_read_b128 v[192:195], v191 offset:1024
	ds_read_b128 v[204:207], v191 offset:2048
	ds_read_b128 v[208:211], v191 offset:3072
	ds_read_b128 v[212:215], v191 offset:4096
	ds_read_b128 v[216:219], v191 offset:5120
	ds_read_b128 v[220:223], v191 offset:6144
	ds_read_b128 v[224:227], v191 offset:7168
	s_add_u32 s24, s34, s10
	s_addc_u32 s25, s35, s11
	s_add_u32 s24, s24, 0x100
	s_addc_u32 s25, s25, 0
	s_add_u32 s101, s60, s10
	s_addc_u32 s74, s61, s11
	s_cmpk_eq_i32 s10, 0xf00
	s_cselect_b32 s31, s27, s25
	s_cselect_b32 s30, s62, s24
	s_cselect_b32 s25, s15, s74
	s_cselect_b32 s24, s63, s101
	v_lshl_add_u64 v[186:187], v[132:133], 0, s[10:11]
	s_add_i32 m0, s48, 0xc000
	s_nop 0
	global_load_lds_dwordx4 v[186:187], off
	v_lshl_add_u64 v[186:187], v[134:135], 0, s[10:11]
	s_add_i32 m0, s48, 0xe000
	s_nop 0
	global_load_lds_dwordx4 v[186:187], off
	s_waitcnt vmcnt(8)
	s_waitcnt lgkmcnt(0)
	s_barrier
	s_setprio 1
	s_waitcnt lgkmcnt(0)
	v_mfma_f32_16x16x32_bf16 v[128:131], v[136:139], v[182:185], v[128:131]
	v_mfma_f32_16x16x32_bf16 v[124:127], v[144:147], v[182:185], v[124:127]
	v_mfma_f32_16x16x32_bf16 v[120:123], v[136:139], v[204:207], v[120:123]
	v_mfma_f32_16x16x32_bf16 v[116:119], v[144:147], v[204:207], v[116:119]
	v_mfma_f32_16x16x32_bf16 v[112:115], v[136:139], v[212:215], v[112:115]
	v_mfma_f32_16x16x32_bf16 v[108:111], v[144:147], v[212:215], v[108:111]
	v_mfma_f32_16x16x32_bf16 v[104:107], v[136:139], v[220:223], v[104:107]
	v_mfma_f32_16x16x32_bf16 v[100:103], v[144:147], v[220:223], v[100:103]
	v_mfma_f32_16x16x32_bf16 v[128:131], v[140:143], v[192:195], v[128:131]
	v_mfma_f32_16x16x32_bf16 v[124:127], v[148:151], v[192:195], v[124:127]
	v_mfma_f32_16x16x32_bf16 v[120:123], v[140:143], v[208:211], v[120:123]
	v_mfma_f32_16x16x32_bf16 v[116:119], v[148:151], v[208:211], v[116:119]
	v_mfma_f32_16x16x32_bf16 v[112:115], v[140:143], v[216:219], v[112:115]
	v_mfma_f32_16x16x32_bf16 v[108:111], v[148:151], v[216:219], v[108:111]
	v_mfma_f32_16x16x32_bf16 v[104:107], v[140:143], v[224:227], v[104:107]
	v_mfma_f32_16x16x32_bf16 v[100:103], v[148:151], v[224:227], v[100:103]
	s_setprio 0
	s_setprio 1
	v_mfma_f32_16x16x32_bf16 v[96:99], v[152:155], v[182:185], v[96:99]
	v_mfma_f32_16x16x32_bf16 v[92:95], v[174:177], v[182:185], v[92:95]
	v_mfma_f32_16x16x32_bf16 v[88:91], v[152:155], v[204:207], v[88:91]
	v_mfma_f32_16x16x32_bf16 v[84:87], v[174:177], v[204:207], v[84:87]
	v_mfma_f32_16x16x32_bf16 v[80:83], v[152:155], v[212:215], v[80:83]
	v_mfma_f32_16x16x32_bf16 v[76:79], v[174:177], v[212:215], v[76:79]
	v_mfma_f32_16x16x32_bf16 v[72:75], v[152:155], v[220:223], v[72:75]
	v_mfma_f32_16x16x32_bf16 v[68:71], v[174:177], v[220:223], v[68:71]
	v_mfma_f32_16x16x32_bf16 v[96:99], v[170:173], v[192:195], v[96:99]
	v_mfma_f32_16x16x32_bf16 v[92:95], v[178:181], v[192:195], v[92:95]
	v_mfma_f32_16x16x32_bf16 v[88:91], v[170:173], v[208:211], v[88:91]
	v_mfma_f32_16x16x32_bf16 v[84:87], v[178:181], v[208:211], v[84:87]
	v_mfma_f32_16x16x32_bf16 v[80:83], v[170:173], v[216:219], v[80:83]
	v_mfma_f32_16x16x32_bf16 v[76:79], v[178:181], v[216:219], v[76:79]
	v_mfma_f32_16x16x32_bf16 v[72:75], v[170:173], v[224:227], v[72:75]
	v_mfma_f32_16x16x32_bf16 v[68:71], v[178:181], v[224:227], v[68:71]
	s_setprio 0
	s_barrier
	s_add_i32 s74, s75, s47
	v_lshl_add_u64 v[186:187], s[24:25], 0, v[2:3]
	s_mov_b32 m0, s74
	ds_read_b128 v[182:185], v191 offset:16384
	ds_read_b128 v[192:195], v191 offset:17408
	ds_read_b128 v[204:207], v191 offset:18432
	ds_read_b128 v[208:211], v191 offset:19456
	ds_read_b128 v[212:215], v191 offset:20480
	ds_read_b128 v[216:219], v191 offset:21504
	ds_read_b128 v[220:223], v191 offset:22528
	ds_read_b128 v[224:227], v191 offset:23552
	global_load_lds_dwordx4 v[186:187], off
	s_add_i32 m0, s74, 0x2000
	s_add_u32 s74, s24, 0x80000
	v_lshl_add_u64 v[196:197], s[24:25], 0, v[156:157]
	s_addc_u32 s75, s25, 0
	s_add_i32 s67, s67, s47
	global_load_lds_dwordx4 v[196:197], off
	v_lshl_add_u64 v[228:229], s[74:75], 0, v[2:3]
	s_mov_b32 m0, s67
	v_lshl_add_u64 v[230:231], s[30:31], 0, v[158:159]
	global_load_lds_dwordx4 v[228:229], off
	v_lshl_add_u64 v[228:229], s[74:75], 0, v[156:157]
	s_add_i32 m0, s67, 0x2000
	s_nop 0
	global_load_lds_dwordx4 v[228:229], off
	v_lshl_add_u64 v[228:229], s[30:31], 0, v[160:161]
	s_mov_b32 m0, s48
	s_nop 0
	global_load_lds_dwordx4 v[228:229], off
	s_mov_b32 m0, s49
	s_nop 0
	global_load_lds_dwordx4 v[230:231], off
	s_waitcnt vmcnt(8)
	s_waitcnt lgkmcnt(0)
	s_barrier
	s_setprio 1
	s_waitcnt lgkmcnt(0)
	v_mfma_f32_16x16x32_bf16 v[64:67], v[136:139], v[182:185], v[64:67]
	v_mfma_f32_16x16x32_bf16 v[60:63], v[144:147], v[182:185], v[60:63]
	v_mfma_f32_16x16x32_bf16 v[56:59], v[136:139], v[204:207], v[56:59]
	v_mfma_f32_16x16x32_bf16 v[52:55], v[144:147], v[204:207], v[52:55]
	v_mfma_f32_16x16x32_bf16 v[48:51], v[136:139], v[212:215], v[48:51]
	v_mfma_f32_16x16x32_bf16 v[44:47], v[144:147], v[212:215], v[44:47]
	v_mfma_f32_16x16x32_bf16 v[40:43], v[136:139], v[220:223], v[40:43]
	v_mfma_f32_16x16x32_bf16 v[36:39], v[144:147], v[220:223], v[36:39]
	v_mfma_f32_16x16x32_bf16 v[64:67], v[140:143], v[192:195], v[64:67]
	v_mfma_f32_16x16x32_bf16 v[60:63], v[148:151], v[192:195], v[60:63]
	v_mfma_f32_16x16x32_bf16 v[56:59], v[140:143], v[208:211], v[56:59]
	v_mfma_f32_16x16x32_bf16 v[52:55], v[148:151], v[208:211], v[52:55]
	v_mfma_f32_16x16x32_bf16 v[48:51], v[140:143], v[216:219], v[48:51]
	v_mfma_f32_16x16x32_bf16 v[44:47], v[148:151], v[216:219], v[44:47]
	v_mfma_f32_16x16x32_bf16 v[40:43], v[140:143], v[224:227], v[40:43]
	v_mfma_f32_16x16x32_bf16 v[36:39], v[148:151], v[224:227], v[36:39]
	s_setprio 0
	s_setprio 1
	v_mfma_f32_16x16x32_bf16 v[32:35], v[152:155], v[182:185], v[32:35]
	v_mfma_f32_16x16x32_bf16 v[28:31], v[174:177], v[182:185], v[28:31]
	v_mfma_f32_16x16x32_bf16 v[24:27], v[152:155], v[204:207], v[24:27]
	v_mfma_f32_16x16x32_bf16 v[20:23], v[174:177], v[204:207], v[20:23]
	v_mfma_f32_16x16x32_bf16 v[16:19], v[152:155], v[212:215], v[16:19]
	v_mfma_f32_16x16x32_bf16 v[12:15], v[174:177], v[212:215], v[12:15]
	v_mfma_f32_16x16x32_bf16 v[8:11], v[152:155], v[220:223], v[8:11]
	v_mfma_f32_16x16x32_bf16 v[4:7], v[174:177], v[220:223], v[4:7]
	v_mfma_f32_16x16x32_bf16 v[32:35], v[170:173], v[192:195], v[32:35]
	v_mfma_f32_16x16x32_bf16 v[28:31], v[178:181], v[192:195], v[28:31]
	v_mfma_f32_16x16x32_bf16 v[24:27], v[170:173], v[208:211], v[24:27]
	v_mfma_f32_16x16x32_bf16 v[20:23], v[178:181], v[208:211], v[20:23]
	v_mfma_f32_16x16x32_bf16 v[16:19], v[170:173], v[216:219], v[16:19]
	v_mfma_f32_16x16x32_bf16 v[12:15], v[178:181], v[216:219], v[12:15]
	v_mfma_f32_16x16x32_bf16 v[8:11], v[170:173], v[224:227], v[8:11]
	v_mfma_f32_16x16x32_bf16 v[4:7], v[178:181], v[224:227], v[4:7]
	s_setprio 0
	s_barrier
	s_add_i32 s67, 0, 0x18000
	s_add_i32 s74, 0, 0x1c000
	v_add_u32_e32 v148, s67, v189
	v_add_u32_e32 v178, s74, v189
	ds_read_b128 v[136:139], v148
	ds_read_b128 v[140:143], v148 offset:1024
	ds_read_b128 v[144:147], v148 offset:2048
	ds_read_b128 v[148:151], v148 offset:3072
	ds_read_b128 v[152:155], v178
	ds_read_b128 v[170:173], v178 offset:1024
	ds_read_b128 v[174:177], v178 offset:2048
	ds_read_b128 v[178:181], v178 offset:3072
	s_add_u32 s30, s30, 0x80000
	s_addc_u32 s31, s31, 0
	s_mov_b32 m0, s50
	v_lshl_add_u64 v[232:233], s[30:31], 0, v[160:161]
	ds_read_b128 v[182:185], v191 offset:32768
	ds_read_b128 v[192:195], v191 offset:33792
	ds_read_b128 v[204:207], v191 offset:34816
	ds_read_b128 v[208:211], v191 offset:35840
	ds_read_b128 v[212:215], v191 offset:36864
	ds_read_b128 v[216:219], v191 offset:37888
	ds_read_b128 v[220:223], v191 offset:38912
	ds_read_b128 v[224:227], v191 offset:39936
	global_load_lds_dwordx4 v[232:233], off
	v_lshl_add_u64 v[232:233], s[30:31], 0, v[158:159]
	s_mov_b32 m0, s51
	s_nop 0
	global_load_lds_dwordx4 v[232:233], off
	s_waitcnt vmcnt(8)
	s_waitcnt lgkmcnt(0)
	s_barrier
	s_setprio 1
	s_waitcnt lgkmcnt(0)
	v_mfma_f32_16x16x32_bf16 v[128:131], v[136:139], v[182:185], v[128:131]
	v_mfma_f32_16x16x32_bf16 v[124:127], v[144:147], v[182:185], v[124:127]
	v_mfma_f32_16x16x32_bf16 v[120:123], v[136:139], v[204:207], v[120:123]
	v_mfma_f32_16x16x32_bf16 v[116:119], v[144:147], v[204:207], v[116:119]
	v_mfma_f32_16x16x32_bf16 v[112:115], v[136:139], v[212:215], v[112:115]
	v_mfma_f32_16x16x32_bf16 v[108:111], v[144:147], v[212:215], v[108:111]
	v_mfma_f32_16x16x32_bf16 v[104:107], v[136:139], v[220:223], v[104:107]
	v_mfma_f32_16x16x32_bf16 v[100:103], v[144:147], v[220:223], v[100:103]
	v_mfma_f32_16x16x32_bf16 v[128:131], v[140:143], v[192:195], v[128:131]
	v_mfma_f32_16x16x32_bf16 v[124:127], v[148:151], v[192:195], v[124:127]
	v_mfma_f32_16x16x32_bf16 v[120:123], v[140:143], v[208:211], v[120:123]
	v_mfma_f32_16x16x32_bf16 v[116:119], v[148:151], v[208:211], v[116:119]
	v_mfma_f32_16x16x32_bf16 v[112:115], v[140:143], v[216:219], v[112:115]
	v_mfma_f32_16x16x32_bf16 v[108:111], v[148:151], v[216:219], v[108:111]
	v_mfma_f32_16x16x32_bf16 v[104:107], v[140:143], v[224:227], v[104:107]
	v_mfma_f32_16x16x32_bf16 v[100:103], v[148:151], v[224:227], v[100:103]
	s_setprio 0
	s_setprio 1
	v_mfma_f32_16x16x32_bf16 v[96:99], v[152:155], v[182:185], v[96:99]
	v_mfma_f32_16x16x32_bf16 v[92:95], v[174:177], v[182:185], v[92:95]
	v_mfma_f32_16x16x32_bf16 v[88:91], v[152:155], v[204:207], v[88:91]
	v_mfma_f32_16x16x32_bf16 v[84:87], v[174:177], v[204:207], v[84:87]
	v_mfma_f32_16x16x32_bf16 v[80:83], v[152:155], v[212:215], v[80:83]
	v_mfma_f32_16x16x32_bf16 v[76:79], v[174:177], v[212:215], v[76:79]
	v_mfma_f32_16x16x32_bf16 v[72:75], v[152:155], v[220:223], v[72:75]
	v_mfma_f32_16x16x32_bf16 v[68:71], v[174:177], v[220:223], v[68:71]
	v_mfma_f32_16x16x32_bf16 v[96:99], v[170:173], v[192:195], v[96:99]
	v_mfma_f32_16x16x32_bf16 v[92:95], v[178:181], v[192:195], v[92:95]
	v_mfma_f32_16x16x32_bf16 v[88:91], v[170:173], v[208:211], v[88:91]
	v_mfma_f32_16x16x32_bf16 v[84:87], v[178:181], v[208:211], v[84:87]
	v_mfma_f32_16x16x32_bf16 v[80:83], v[170:173], v[216:219], v[80:83]
	v_mfma_f32_16x16x32_bf16 v[76:79], v[178:181], v[216:219], v[76:79]
	v_mfma_f32_16x16x32_bf16 v[72:75], v[170:173], v[224:227], v[72:75]
	v_mfma_f32_16x16x32_bf16 v[68:71], v[178:181], v[224:227], v[68:71]
	s_setprio 0
	s_barrier
	s_add_i32 s30, s67, s47
	v_lshl_add_u64 v[186:187], v[186:187], 0, s[28:29]
	s_mov_b32 m0, s30
	ds_read_b128 v[182:185], v191 offset:49152
	ds_read_b128 v[192:195], v191 offset:50176
	ds_read_b128 v[204:207], v191 offset:51200
	ds_read_b128 v[208:211], v191 offset:52224
	ds_read_b128 v[212:215], v191 offset:53248
	ds_read_b128 v[216:219], v191 offset:54272
	ds_read_b128 v[220:223], v191 offset:55296
	ds_read_b128 v[224:227], v191 offset:56320
	global_load_lds_dwordx4 v[186:187], off
	s_add_i32 m0, s30, 0x2000
	s_add_u32 s24, s24, 0x80080
	v_lshl_add_u64 v[186:187], v[196:197], 0, s[28:29]
	s_addc_u32 s25, s25, 0
	s_add_i32 s30, s74, s47
	global_load_lds_dwordx4 v[186:187], off
	v_lshl_add_u64 v[186:187], s[24:25], 0, v[2:3]
	s_mov_b32 m0, s30
	s_nop 0
	global_load_lds_dwordx4 v[186:187], off
	v_lshl_add_u64 v[186:187], s[24:25], 0, v[156:157]
	s_add_i32 m0, s30, 0x2000
	s_nop 0
	global_load_lds_dwordx4 v[186:187], off
	v_lshl_add_u64 v[186:187], v[228:229], 0, s[28:29]
	s_mov_b32 m0, s52
	s_nop 0
	global_load_lds_dwordx4 v[186:187], off
	v_lshl_add_u64 v[186:187], v[230:231], 0, s[28:29]
	s_mov_b32 m0, s53
	s_nop 0
	global_load_lds_dwordx4 v[186:187], off
	s_waitcnt vmcnt(8)
	s_waitcnt lgkmcnt(0)
	s_barrier
	s_setprio 1
	s_waitcnt lgkmcnt(0)
	v_mfma_f32_16x16x32_bf16 v[64:67], v[136:139], v[182:185], v[64:67]
	v_mfma_f32_16x16x32_bf16 v[60:63], v[144:147], v[182:185], v[60:63]
	v_mfma_f32_16x16x32_bf16 v[56:59], v[136:139], v[204:207], v[56:59]
	v_mfma_f32_16x16x32_bf16 v[52:55], v[144:147], v[204:207], v[52:55]
	v_mfma_f32_16x16x32_bf16 v[48:51], v[136:139], v[212:215], v[48:51]
	v_mfma_f32_16x16x32_bf16 v[44:47], v[144:147], v[212:215], v[44:47]
	v_mfma_f32_16x16x32_bf16 v[40:43], v[136:139], v[220:223], v[40:43]
	v_mfma_f32_16x16x32_bf16 v[36:39], v[144:147], v[220:223], v[36:39]
	v_mfma_f32_16x16x32_bf16 v[64:67], v[140:143], v[192:195], v[64:67]
	v_mfma_f32_16x16x32_bf16 v[60:63], v[148:151], v[192:195], v[60:63]
	v_mfma_f32_16x16x32_bf16 v[56:59], v[140:143], v[208:211], v[56:59]
	v_mfma_f32_16x16x32_bf16 v[52:55], v[148:151], v[208:211], v[52:55]
	v_mfma_f32_16x16x32_bf16 v[48:51], v[140:143], v[216:219], v[48:51]
	v_mfma_f32_16x16x32_bf16 v[44:47], v[148:151], v[216:219], v[44:47]
	v_mfma_f32_16x16x32_bf16 v[40:43], v[140:143], v[224:227], v[40:43]
	v_mfma_f32_16x16x32_bf16 v[36:39], v[148:151], v[224:227], v[36:39]
	s_setprio 0
	s_setprio 1
	v_mfma_f32_16x16x32_bf16 v[32:35], v[152:155], v[182:185], v[32:35]
	v_mfma_f32_16x16x32_bf16 v[28:31], v[174:177], v[182:185], v[28:31]
	v_mfma_f32_16x16x32_bf16 v[24:27], v[152:155], v[204:207], v[24:27]
	v_mfma_f32_16x16x32_bf16 v[20:23], v[174:177], v[204:207], v[20:23]
	v_mfma_f32_16x16x32_bf16 v[16:19], v[152:155], v[212:215], v[16:19]
	v_mfma_f32_16x16x32_bf16 v[12:15], v[174:177], v[212:215], v[12:15]
	v_mfma_f32_16x16x32_bf16 v[8:11], v[152:155], v[220:223], v[8:11]
	v_mfma_f32_16x16x32_bf16 v[4:7], v[174:177], v[220:223], v[4:7]
	v_mfma_f32_16x16x32_bf16 v[32:35], v[170:173], v[192:195], v[32:35]
	v_mfma_f32_16x16x32_bf16 v[28:31], v[178:181], v[192:195], v[28:31]
	v_mfma_f32_16x16x32_bf16 v[24:27], v[170:173], v[208:211], v[24:27]
	v_mfma_f32_16x16x32_bf16 v[20:23], v[178:181], v[208:211], v[20:23]
	v_mfma_f32_16x16x32_bf16 v[16:19], v[170:173], v[216:219], v[16:19]
	v_mfma_f32_16x16x32_bf16 v[12:15], v[178:181], v[216:219], v[12:15]
	v_mfma_f32_16x16x32_bf16 v[8:11], v[170:173], v[224:227], v[8:11]
	v_mfma_f32_16x16x32_bf16 v[4:7], v[178:181], v[224:227], v[4:7]
	s_setprio 0
	s_barrier
	s_add_i32 s66, s66, 2
	s_add_u32 s10, s10, 0x100
	s_addc_u32 s11, s11, 0
	s_cmp_gt_u32 s66, 29
	s_cbranch_scc0 .LBB0_866
	s_and_b64 vcc, exec, s[12:13]
	s_cbranch_vccz .LBB0_869
	s_barrier
